# attention loop: one lgkmcnt wait per MFMA pair instead of per MFMA
# speedup vs baseline: 1.0199x; 1.0049x over previous
; #define LAS __attribute__((address_space(3)))
; __device__ __forceinline__ void attn_unit(const bf16_t* Q, const bf16_t* K, const bf16_t* Vt, int ntiles, int nrows, bf16_t* O, float negM, LAS unsigned char* lds, int tid) {
;     const int lane = tid & 63, w = tid >> 6, r32 = lane & 31, hi = lane >> 5;
;     const int row0 = w * 64 + r32, row1 = row0 + 32;
;     bf16x8 qa[4], qb[4];
;     {
;         const bf16_t* qp0 = Q + (size_t)min(row0, nrows - 1) * 64 + hi * 8;
;         const bf16_t* qp1 = Q + (size_t)min(row1, nrows - 1) * 64 + hi * 8;
; #pragma unroll
;         for (int s = 0; s < 4; ++s) { qa[s] = *(const bf16x8*)(qp0 + 16 * s); qb[s] = *(const bf16x8*)(qp1 + 16 * s); }
;     }
;     LAS unsigned char* qlds = lds + 40960 + w * 4096 + lane * 16;
; #pragma unroll
;     for (int s = 0; s < 4; ++s) *(LAS bf16x8*)(qlds + s * 1024) = qb[s];
;     f32x16 oa0, oa1, ob0, ob1;
; #pragma unroll
;     for (int e = 0; e < 16; ++e) { oa0[e] = 0.f; oa1[e] = 0.f; ob0[e] = 0.f; ob1[e] = 0.f; }
;     float lsa = 0.f, lsb = 0.f;
;     const int srow = tid >> 3, sch = tid & 7;
;     const bf16_t* kg = K + srow * 64 + sch * 8;
;     const bf16_t* vg = Vt + (size_t)srow * TKV + sch * 8;
;     const int soff = srow * 144 + sch * 16;
;     u32x4 kr = *(const u32x4*)kg, vr = *(const u32x4*)vg;
;     *(LAS u32x4*)(lds + soff) = kr; *(LAS u32x4*)(lds + 9216 + soff) = vr;
;     __syncthreads();
;     const int foff = r32 * 144 + hi * 16;
.LBB0_478:
	s_add_i32 s4, s7, 0xfffffe00
	s_cmpk_lt_i32 s7, 0x200
	s_cselect_b64 s[0:1], -1, 0
	s_and_b64 s[0:1], s[0:1], exec
	s_cselect_b32 s4, s7, s4
	s_cselect_b32 s8, s14, 0x100
	s_cselect_b32 s13, 0x44, 4
	s_lshl_b32 s0, s4, 9
	s_and_b32 s9, s0, 0xe00
	s_or_b32 s5, s9, 0x100
	s_cmpk_lt_i32 s7, 0x200
	s_cselect_b64 s[0:1], -1, 0
	s_and_b64 s[0:1], s[0:1], exec
	s_cselect_b32 s28, s5, 0
	s_ashr_i32 s10, s4, 3
	s_cmpk_lt_i32 s7, 0x200
	s_cselect_b64 s[0:1], -1, 0
	s_and_b64 s[0:1], s[0:1], exec
	s_cselect_b32 s29, s10, s7
	s_ashr_i32 s12, s7, 6
	s_cmpk_lt_i32 s7, 0x200
	s_cselect_b64 s[0:1], -1, 0
	s_and_b64 s[4:5], s[0:1], exec
	s_cselect_b32 s5, s12, s10
	s_and_b32 s11, s29, 7
	s_bfe_u32 s4, s29, 0x10002
	s_lshl_b32 s29, s5, 3
	s_or_b32 s29, s29, s11
	s_mul_hi_i32 s30, s29, 0x1100
	s_mulk_i32 s29, 0x1100
	s_add_u32 s28, s29, s28
	s_addc_u32 s29, s30, 0
	s_lshl_b64 s[28:29], s[28:29], 7
	s_add_u32 s28, s34, s28
	s_addc_u32 s29, s35, s29
	s_add_i32 s31, s8, -1
	v_min_i32_e32 v16, s31, v170
	v_ashrrev_i32_e32 v17, 31, v16
	v_lshlrev_b64 v[16:17], 7, v[16:17]
	v_lshl_add_u64 v[16:17], s[28:29], 0, v[16:17]
	v_lshl_add_u64 v[28:29], v[16:17], 0, v[186:187]
	v_min_i32_e32 v16, s31, v172
	v_ashrrev_i32_e32 v17, 31, v16
	v_lshlrev_b64 v[16:17], 7, v[16:17]
	v_lshl_add_u64 v[16:17], s[28:29], 0, v[16:17]
	v_lshl_add_u64 v[30:31], v[16:17], 0, v[186:187]
	global_load_dwordx4 v[146:149], v[28:29], off
	global_load_dwordx4 v[150:153], v[28:29], off offset:32
	global_load_dwordx4 v[154:157], v[28:29], off offset:64
	global_load_dwordx4 v[158:161], v[28:29], off offset:96
	global_load_dwordx4 v[96:99], v[30:31], off
	global_load_dwordx4 v[100:103], v[30:31], off offset:32
	global_load_dwordx4 v[104:107], v[30:31], off offset:64
	global_load_dwordx4 v[108:111], v[30:31], off offset:96
	s_lshl_b32 s5, s5, 1
	s_or_b32 s30, s4, s5
	v_mad_i64_i32 v[112:113], s[28:29], s30, v233, v[174:175]
	v_mad_i64_i32 v[114:115], s[28:29], s30, v233, v[176:177]
	global_load_dwordx4 v[162:165], v[112:113], off
	global_load_dwordx4 v[166:169], v[114:115], off
	v_mad_i64_i32 v[196:197], s[4:5], s30, v233, v[184:185]
	v_mad_i64_i32 v[198:199], s[4:5], s30, v233, v[192:193]
	v_mov_b32_e32 v173, v181
	s_movk_i32 s28, 0x4800
	v_add_u32_e32 v188, s28, v181
	s_mov_b32 s29, 0
	v_mov_b32_e32 v194, 0
	v_mov_b32_e32 v195, 0
	v_mov_b32_e32 v226, 0
	v_mov_b32_e32 v227, 0
	v_mov_b32_e32 v246, 0
	v_mov_b32_e32 v247, 0
	v_mov_b32_e32 v16, 0
	v_mov_b32_e32 v17, 0
	v_mov_b32_e32 v18, 0
	v_mov_b32_e32 v19, 0
	v_mov_b32_e32 v20, 0
	v_mov_b32_e32 v21, 0
	v_mov_b32_e32 v22, 0
	v_mov_b32_e32 v23, 0
	v_mov_b32_e32 v24, 0
	v_mov_b32_e32 v25, 0
	v_mov_b32_e32 v26, 0
	v_mov_b32_e32 v27, 0
	v_mov_b32_e32 v28, 0
	v_mov_b32_e32 v29, 0
	v_mov_b32_e32 v30, 0
	v_mov_b32_e32 v31, 0
	v_mov_b32_e32 v32, 0
	v_mov_b32_e32 v33, 0
	v_mov_b32_e32 v34, 0
	v_mov_b32_e32 v35, 0
	v_mov_b32_e32 v36, 0
	v_mov_b32_e32 v37, 0
	v_mov_b32_e32 v38, 0
	v_mov_b32_e32 v39, 0
	v_mov_b32_e32 v40, 0
	v_mov_b32_e32 v41, 0
	v_mov_b32_e32 v42, 0
	v_mov_b32_e32 v43, 0
	v_mov_b32_e32 v44, 0
	v_mov_b32_e32 v45, 0
	v_mov_b32_e32 v46, 0
	v_mov_b32_e32 v47, 0
	v_mov_b32_e32 v48, 0
	v_mov_b32_e32 v49, 0
	v_mov_b32_e32 v50, 0
	v_mov_b32_e32 v51, 0
	v_mov_b32_e32 v52, 0
	v_mov_b32_e32 v53, 0
	v_mov_b32_e32 v54, 0
	v_mov_b32_e32 v55, 0
	v_mov_b32_e32 v56, 0
	v_mov_b32_e32 v57, 0
	v_mov_b32_e32 v58, 0
	v_mov_b32_e32 v59, 0
	v_mov_b32_e32 v60, 0
	v_mov_b32_e32 v61, 0
	v_mov_b32_e32 v62, 0
	v_mov_b32_e32 v63, 0
	v_mov_b32_e32 v64, 0
	v_mov_b32_e32 v65, 0
	v_mov_b32_e32 v66, 0
	v_mov_b32_e32 v67, 0
	v_mov_b32_e32 v68, 0
	v_mov_b32_e32 v69, 0
	v_mov_b32_e32 v70, 0
	v_mov_b32_e32 v71, 0
	v_mov_b32_e32 v72, 0
	v_mov_b32_e32 v73, 0
	v_mov_b32_e32 v74, 0
	v_mov_b32_e32 v75, 0
	v_mov_b32_e32 v76, 0
	v_mov_b32_e32 v77, 0
	v_mov_b32_e32 v78, 0
	v_mov_b32_e32 v79, 0
	v_mov_b32_e32 v238, 0
	v_mov_b32_e32 v239, 0
	v_mov_b32_e32 v240, 0
	v_mov_b32_e32 v241, 0
	v_mov_b32_e32 v242, 0
	v_mov_b32_e32 v243, 0
	v_mov_b32_e32 v244, 0
	v_mov_b32_e32 v245, 0
	s_waitcnt vmcnt(0)
	ds_write_b128 v145, v[162:165]
	ds_write_b128 v145, v[166:169] offset:9216
	global_load_dwordx4 v[162:165], v[198:199], off
	global_load_dwordx4 v[166:169], v[196:197], off
	v_lshl_add_u64 v[198:199], v[198:199], 0, s[80:81]
	v_lshl_add_u64 v[196:197], v[196:197], 0, s[44:45]
	s_waitcnt lgkmcnt(0)
	s_barrier
	ds_read_b128 v[80:83], v173
	ds_read_b128 v[84:87], v173 offset:32
	ds_read_b128 v[88:91], v173 offset:64
	ds_read_b128 v[92:95], v173 offset:96
	ds_read_b128 v[200:203], v173 offset:9280
	ds_read_b128 v[204:207], v173 offset:13888
	ds_read_b128 v[208:211], v173 offset:9312
	ds_read_b128 v[212:215], v173 offset:13920
	s_waitcnt lgkmcnt(7)
	v_mfma_f32_32x32x16_bf16 v[112:127], v[80:83], v[146:149], v[0:15]
	s_waitcnt lgkmcnt(6)
	v_mfma_f32_32x32x16_bf16 v[112:127], v[84:87], v[150:153], v[112:127]
	s_waitcnt lgkmcnt(5)
	v_mfma_f32_32x32x16_bf16 v[112:127], v[88:91], v[154:157], v[112:127]
	s_waitcnt lgkmcnt(4)
	v_mfma_f32_32x32x16_bf16 v[112:127], v[92:95], v[158:161], v[112:127]
	s_waitcnt lgkmcnt(0)
	s_nop 7
	s_nop 3
; #define LAS __attribute__((address_space(3)))
; __device__ __forceinline__ void attn_unit(const bf16_t* Q, const bf16_t* K, const bf16_t* Vt, int ntiles, int nrows, bf16_t* O, float negM, LAS unsigned char* lds, int tid) {
;     ...
;     for (int t = 0; t < ntiles; ++t) {
;         const int cur = t & 1;
;         const bool more = (t + 1 < ntiles);
;         if (more) { kr = *(const u32x4*)(kg + (size_t)(t + 1) * 4096); vr = *(const u32x4*)(vg + (size_t)(t + 1) * 64); }
;         const LAS unsigned char* kb = lds + cur * 18432 + foff;
;         const LAS unsigned char* vb = kb + 9216;
;         bf16x8 kf0[4], kf1[4];
; #pragma unroll
;         for (int s = 0; s < 4; ++s) { kf0[s] = *(const LAS bf16x8*)(kb + s * 32); kf1[s] = *(const LAS bf16x8*)(kb + 32 * 144 + s * 32); }
;         bf16x8 pa[4], pb[4];
;         ATT_SCORES(qa, pa, lsa);
;         bf16x8 qc[4];
; #pragma unroll
;         for (int s = 0; s < 4; ++s) qc[s] = *(const LAS bf16x8*)(qlds + s * 1024);
;         ATT_SCORES(qc, pb, lsb);
; #pragma unroll
;         for (int s = 0; s < 4; ++s) {
;             const bf16x8 v0 = *(const LAS bf16x8*)(vb + s * 32), v1 = *(const LAS bf16x8*)(vb + 32 * 144 + s * 32);
;             oa0 = __builtin_amdgcn_mfma_f32_32x32x16_bf16(v0, pa[s], oa0, 0, 0, 0);
;             oa1 = __builtin_amdgcn_mfma_f32_32x32x16_bf16(v1, pa[s], oa1, 0, 0, 0);
;             ob0 = __builtin_amdgcn_mfma_f32_32x32x16_bf16(v0, pb[s], ob0, 0, 0, 0);
;             ob1 = __builtin_amdgcn_mfma_f32_32x32x16_bf16(v1, pb[s], ob1, 0, 0, 0);
;         }
;         if (more) { *(LAS u32x4*)(lds + (cur ^ 1) * 18432 + soff) = kr; *(LAS u32x4*)(lds + (cur ^ 1) * 18432 + 9216 + soff) = vr; }
.Lattn_tile:
	v_mfma_f32_32x32x16_bf16 v[128:143], v[80:83], v[96:99], v[0:15]
	ds_read_b128 v[80:83], v173 offset:4608
	v_exp_f32_e32 v112, v112
	v_exp_f32_e32 v113, v113
	v_mfma_f32_32x32x16_bf16 v[16:31], v[200:203], v[238:241], v[16:31]
	ds_read_b128 v[200:203], v173 offset:9216
	v_exp_f32_e32 v114, v114
	v_exp_f32_e32 v115, v115
	v_cvt_pk_bf16_f32 v216, v112, v113
	v_add_f32_e32 v194, v194, v112
	v_add_f32_e32 v226, v226, v113
	v_mfma_f32_32x32x16_bf16 v[128:143], v[84:87], v[100:103], v[128:143]
	ds_read_b128 v[84:87], v173 offset:4640
	v_exp_f32_e32 v116, v116
	v_exp_f32_e32 v117, v117
	v_cvt_pk_bf16_f32 v217, v114, v115
	v_add_f32_e32 v194, v194, v114
	v_add_f32_e32 v226, v226, v115
	v_mfma_f32_32x32x16_bf16 v[32:47], v[204:207], v[238:241], v[32:47]
	ds_read_b128 v[204:207], v173 offset:13824
	v_exp_f32_e32 v118, v118
	v_exp_f32_e32 v119, v119
	v_cvt_pk_bf16_f32 v218, v116, v117
	v_add_f32_e32 v194, v194, v116
	v_add_f32_e32 v226, v226, v117
	v_mfma_f32_32x32x16_bf16 v[128:143], v[88:91], v[104:107], v[128:143]
	ds_read_b128 v[88:91], v173 offset:4672
	v_exp_f32_e32 v120, v120
	v_exp_f32_e32 v121, v121
	v_cvt_pk_bf16_f32 v219, v118, v119
	v_add_f32_e32 v194, v194, v118
	v_add_f32_e32 v226, v226, v119
	v_mfma_f32_32x32x16_bf16 v[16:31], v[208:211], v[242:245], v[16:31]
	ds_read_b128 v[208:211], v173 offset:9248
	v_exp_f32_e32 v122, v122
	v_exp_f32_e32 v123, v123
	v_cvt_pk_bf16_f32 v234, v120, v121
	v_add_f32_e32 v194, v194, v120
	v_add_f32_e32 v226, v226, v121
	v_mfma_f32_32x32x16_bf16 v[128:143], v[92:95], v[108:111], v[128:143]
	ds_read_b128 v[92:95], v173 offset:4704
	v_exp_f32_e32 v124, v124
	v_exp_f32_e32 v125, v125
	v_cvt_pk_bf16_f32 v235, v122, v123
	v_add_f32_e32 v194, v194, v122
	v_add_f32_e32 v226, v226, v123
	v_mfma_f32_32x32x16_bf16 v[32:47], v[212:215], v[242:245], v[32:47]
	ds_read_b128 v[212:215], v173 offset:13856
	v_exp_f32_e32 v126, v126
	v_exp_f32_e32 v127, v127
	v_cvt_pk_bf16_f32 v236, v124, v125
	v_add_f32_e32 v194, v194, v124
	v_add_f32_e32 v226, v226, v125
	v_cvt_pk_bf16_f32 v237, v126, v127
	v_add_f32_e32 v194, v194, v126
	v_add_f32_e32 v226, v226, v127
	s_waitcnt vmcnt(0)
	v_add_u32_e32 v189, s28, v145
	ds_write_b128 v189, v[162:165]
	ds_write_b128 v189, v[166:169] offset:9216
	s_waitcnt lgkmcnt(8)
	v_mfma_f32_32x32x16_bf16 v[112:127], v[80:83], v[146:149], v[0:15]
	v_exp_f32_e32 v128, v128
	v_exp_f32_e32 v129, v129
	v_mfma_f32_32x32x16_bf16 v[48:63], v[200:203], v[216:219], v[48:63]
	v_exp_f32_e32 v130, v130
	v_exp_f32_e32 v131, v131
	v_cvt_pk_bf16_f32 v238, v128, v129
	v_add_f32_e32 v195, v195, v128
	v_add_f32_e32 v227, v227, v129
	s_waitcnt lgkmcnt(6)
	v_mfma_f32_32x32x16_bf16 v[112:127], v[84:87], v[150:153], v[112:127]
	v_exp_f32_e32 v132, v132
	v_exp_f32_e32 v133, v133
	v_cvt_pk_bf16_f32 v239, v130, v131
	v_add_f32_e32 v195, v195, v130
	v_add_f32_e32 v227, v227, v131
	v_mfma_f32_32x32x16_bf16 v[64:79], v[204:207], v[216:219], v[64:79]
	v_exp_f32_e32 v134, v134
	v_exp_f32_e32 v135, v135
	v_cvt_pk_bf16_f32 v240, v132, v133
	v_add_f32_e32 v195, v195, v132
	v_add_f32_e32 v227, v227, v133
	s_waitcnt lgkmcnt(4)
	v_mfma_f32_32x32x16_bf16 v[112:127], v[88:91], v[154:157], v[112:127]
	v_exp_f32_e32 v136, v136
	v_exp_f32_e32 v137, v137
	v_cvt_pk_bf16_f32 v241, v134, v135
	v_add_f32_e32 v195, v195, v134
	v_add_f32_e32 v227, v227, v135
	v_mfma_f32_32x32x16_bf16 v[48:63], v[208:211], v[234:237], v[48:63]
	v_exp_f32_e32 v138, v138
	v_exp_f32_e32 v139, v139
	v_cvt_pk_bf16_f32 v242, v136, v137
	v_add_f32_e32 v195, v195, v136
	v_add_f32_e32 v227, v227, v137
	s_waitcnt lgkmcnt(2)
	v_mfma_f32_32x32x16_bf16 v[112:127], v[92:95], v[158:161], v[112:127]
	v_exp_f32_e32 v140, v140
	v_exp_f32_e32 v141, v141
	v_cvt_pk_bf16_f32 v243, v138, v139
	v_add_f32_e32 v195, v195, v138
	v_add_f32_e32 v227, v227, v139
	v_mfma_f32_32x32x16_bf16 v[64:79], v[212:215], v[234:237], v[64:79]
	v_exp_f32_e32 v142, v142
	v_exp_f32_e32 v143, v143
	v_cvt_pk_bf16_f32 v244, v140, v141
	v_add_f32_e32 v195, v195, v140
	v_add_f32_e32 v227, v227, v141
	v_cvt_pk_bf16_f32 v245, v142, v143
	v_add_f32_e32 v195, v195, v142
	v_add_f32_e32 v227, v227, v143
	s_waitcnt lgkmcnt(0)
	s_barrier
; #define LAS __attribute__((address_space(3)))
; __device__ __forceinline__ void attn_unit(const bf16_t* Q, const bf16_t* K, const bf16_t* Vt, int ntiles, int nrows, bf16_t* O, float negM, LAS unsigned char* lds, int tid) {
;     ...
;     for (int t = 0; t < ntiles; ++t) {
;         const int cur = t & 1;
;         const bool more = (t + 1 < ntiles);
;         if (more) { kr = *(const u32x4*)(kg + (size_t)(t + 1) * 4096); vr = *(const u32x4*)(vg + (size_t)(t + 1) * 64); }
;         const LAS unsigned char* kb = lds + cur * 18432 + foff;
;         const LAS unsigned char* vb = kb + 9216;
;         bf16x8 kf0[4], kf1[4];
; #pragma unroll
;         for (int s = 0; s < 4; ++s) { kf0[s] = *(const LAS bf16x8*)(kb + s * 32); kf1[s] = *(const LAS bf16x8*)(kb + 32 * 144 + s * 32); }
;         bf16x8 pa[4], pb[4];
;         ATT_SCORES(qa, pa, lsa);
;         bf16x8 qc[4];
; #pragma unroll
;         for (int s = 0; s < 4; ++s) qc[s] = *(const LAS bf16x8*)(qlds + s * 1024);
;         ATT_SCORES(qc, pb, lsb);
; #pragma unroll
;         for (int s = 0; s < 4; ++s) {
;             const bf16x8 v0 = *(const LAS bf16x8*)(vb + s * 32), v1 = *(const LAS bf16x8*)(vb + 32 * 144 + s * 32);
;             oa0 = __builtin_amdgcn_mfma_f32_32x32x16_bf16(v0, pa[s], oa0, 0, 0, 0);
;             oa1 = __builtin_amdgcn_mfma_f32_32x32x16_bf16(v1, pa[s], oa1, 0, 0, 0);
;             ob0 = __builtin_amdgcn_mfma_f32_32x32x16_bf16(v0, pb[s], ob0, 0, 0, 0);
;             ob1 = __builtin_amdgcn_mfma_f32_32x32x16_bf16(v1, pb[s], ob1, 0, 0, 0);
;         }
;         if (more) { *(LAS u32x4*)(lds + (cur ^ 1) * 18432 + soff) = kr; *(LAS u32x4*)(lds + (cur ^ 1) * 18432 + 9216 + soff) = vr; }
;         __syncthreads();
;     }
	global_load_dwordx4 v[162:165], v[198:199], off
	global_load_dwordx4 v[166:169], v[196:197], off
	v_lshl_add_u64 v[198:199], v[198:199], 0, s[80:81]
	v_lshl_add_u64 v[196:197], v[196:197], 0, s[44:45]
	v_mfma_f32_32x32x16_bf16 v[128:143], v[80:83], v[96:99], v[0:15]
	ds_read_b128 v[80:83], v188
	v_exp_f32_e32 v112, v112
	v_exp_f32_e32 v113, v113
	v_mfma_f32_32x32x16_bf16 v[16:31], v[200:203], v[238:241], v[16:31]
	ds_read_b128 v[200:203], v173 offset:9280
	v_exp_f32_e32 v114, v114
	v_exp_f32_e32 v115, v115
	v_cvt_pk_bf16_f32 v216, v112, v113
	v_add_f32_e32 v194, v194, v112
	v_add_f32_e32 v226, v226, v113
	v_mfma_f32_32x32x16_bf16 v[128:143], v[84:87], v[100:103], v[128:143]
	ds_read_b128 v[84:87], v188 offset:32
	v_exp_f32_e32 v116, v116
	v_exp_f32_e32 v117, v117
	v_cvt_pk_bf16_f32 v217, v114, v115
	v_add_f32_e32 v194, v194, v114
	v_add_f32_e32 v226, v226, v115
	v_mfma_f32_32x32x16_bf16 v[32:47], v[204:207], v[238:241], v[32:47]
	ds_read_b128 v[204:207], v173 offset:13888
	v_exp_f32_e32 v118, v118
	v_exp_f32_e32 v119, v119
	v_cvt_pk_bf16_f32 v218, v116, v117
	v_add_f32_e32 v194, v194, v116
	v_add_f32_e32 v226, v226, v117
	v_mfma_f32_32x32x16_bf16 v[128:143], v[88:91], v[104:107], v[128:143]
	ds_read_b128 v[88:91], v188 offset:64
	v_exp_f32_e32 v120, v120
	v_exp_f32_e32 v121, v121
	v_cvt_pk_bf16_f32 v219, v118, v119
	v_add_f32_e32 v194, v194, v118
	v_add_f32_e32 v226, v226, v119
	v_mfma_f32_32x32x16_bf16 v[16:31], v[208:211], v[242:245], v[16:31]
	ds_read_b128 v[208:211], v173 offset:9312
	v_exp_f32_e32 v122, v122
	v_exp_f32_e32 v123, v123
	v_cvt_pk_bf16_f32 v234, v120, v121
	v_add_f32_e32 v194, v194, v120
	v_add_f32_e32 v226, v226, v121
	v_mfma_f32_32x32x16_bf16 v[128:143], v[92:95], v[108:111], v[128:143]
	ds_read_b128 v[92:95], v188 offset:96
	v_exp_f32_e32 v124, v124
	v_exp_f32_e32 v125, v125
	v_cvt_pk_bf16_f32 v235, v122, v123
	v_add_f32_e32 v194, v194, v122
	v_add_f32_e32 v226, v226, v123
	v_mfma_f32_32x32x16_bf16 v[32:47], v[212:215], v[242:245], v[32:47]
	ds_read_b128 v[212:215], v173 offset:13920
	v_exp_f32_e32 v126, v126
	v_exp_f32_e32 v127, v127
	v_cvt_pk_bf16_f32 v236, v124, v125
	v_add_f32_e32 v194, v194, v124
	v_add_f32_e32 v226, v226, v125
	v_cvt_pk_bf16_f32 v237, v126, v127
	v_add_f32_e32 v194, v194, v126
	v_add_f32_e32 v226, v226, v127
	s_waitcnt lgkmcnt(6)
	v_mfma_f32_32x32x16_bf16 v[112:127], v[80:83], v[146:149], v[0:15]
	v_exp_f32_e32 v128, v128
	v_exp_f32_e32 v129, v129
	v_mfma_f32_32x32x16_bf16 v[48:63], v[200:203], v[216:219], v[48:63]
	v_exp_f32_e32 v130, v130
	v_exp_f32_e32 v131, v131
	v_cvt_pk_bf16_f32 v238, v128, v129
	v_add_f32_e32 v195, v195, v128
	v_add_f32_e32 v227, v227, v129
	s_waitcnt lgkmcnt(4)
	v_mfma_f32_32x32x16_bf16 v[112:127], v[84:87], v[150:153], v[112:127]
	v_exp_f32_e32 v132, v132
	v_exp_f32_e32 v133, v133
	v_cvt_pk_bf16_f32 v239, v130, v131
	v_add_f32_e32 v195, v195, v130
	v_add_f32_e32 v227, v227, v131
	v_mfma_f32_32x32x16_bf16 v[64:79], v[204:207], v[216:219], v[64:79]
	v_exp_f32_e32 v134, v134
	v_exp_f32_e32 v135, v135
	v_cvt_pk_bf16_f32 v240, v132, v133
	v_add_f32_e32 v195, v195, v132
	v_add_f32_e32 v227, v227, v133
	s_waitcnt lgkmcnt(2)
	v_mfma_f32_32x32x16_bf16 v[112:127], v[88:91], v[154:157], v[112:127]
	v_exp_f32_e32 v136, v136
	v_exp_f32_e32 v137, v137
	v_cvt_pk_bf16_f32 v241, v134, v135
	v_add_f32_e32 v195, v195, v134
	v_add_f32_e32 v227, v227, v135
	v_mfma_f32_32x32x16_bf16 v[48:63], v[208:211], v[234:237], v[48:63]
	v_exp_f32_e32 v138, v138
	v_exp_f32_e32 v139, v139
	v_cvt_pk_bf16_f32 v242, v136, v137
	v_add_f32_e32 v195, v195, v136
	v_add_f32_e32 v227, v227, v137
	s_waitcnt lgkmcnt(0)
	v_mfma_f32_32x32x16_bf16 v[112:127], v[92:95], v[158:161], v[112:127]
	v_exp_f32_e32 v140, v140
	v_exp_f32_e32 v141, v141
	v_cvt_pk_bf16_f32 v243, v138, v139
	v_add_f32_e32 v195, v195, v138
	v_add_f32_e32 v227, v227, v139
	v_mfma_f32_32x32x16_bf16 v[64:79], v[212:215], v[234:237], v[64:79]
	v_exp_f32_e32 v142, v142
	v_exp_f32_e32 v143, v143
	v_cvt_pk_bf16_f32 v244, v140, v141
	v_add_f32_e32 v195, v195, v140
	v_add_f32_e32 v227, v227, v141
	v_cvt_pk_bf16_f32 v245, v142, v143
	v_add_f32_e32 v195, v195, v142
	v_add_f32_e32 v227, v227, v143
	v_mov_b32_e32 v173, v188
	s_add_i32 s28, s28, 0x4800
	s_cmp_eq_u32 s28, 0xd800
	s_cselect_b32 s28, 0, s28
	v_add_u32_e32 v188, s28, v181
	s_add_i32 s29, s29, 1
	s_cmp_lt_i32 s29, s13
	s_cbranch_scc1 .Lattn_tile
	s_waitcnt lgkmcnt(0)
	s_barrier
	v_mfma_f32_32x32x16_bf16 v[16:31], v[200:203], v[238:241], v[16:31]
	v_mfma_f32_32x32x16_bf16 v[32:47], v[204:207], v[238:241], v[32:47]
	v_mfma_f32_32x32x16_bf16 v[16:31], v[208:211], v[242:245], v[16:31]
	v_mfma_f32_32x32x16_bf16 v[32:47], v[212:215], v[242:245], v[32:47]
	v_add_f32_e32 v194, v194, v226
	v_add_f32_e32 v195, v195, v227
	s_nop 7
	s_nop 3
